# P4 de-phasing: workgroups >= 32 with bit 3 of the block index set (they own two units, 13 us of slack) start 6.8 us later so unit load bursts interleave
# speedup vs baseline: 1.0017x; 1.0017x over previous
.LBB0_2106:
	s_or_b64 exec, exec, s[0:1]
	s_cmpk_gt_i32 s96, 0x21f
	s_waitcnt lgkmcnt(0)
	s_barrier
	s_cbranch_scc1 .LBB0_2180
	s_cmp_lt_u32 s96, 32
	s_cbranch_scc1 .Lstg4_done
	s_bitcmp0_b32 s96, 3
	s_cbranch_scc1 .Lstg4_done
	s_sleep 127
	s_sleep 127
.Lstg4_done:
	s_add_u32 s24, s90, 0xa06ea00
	s_addc_u32 s25, s91, 0
	s_add_u32 s4, s90, 0x1902000
	s_addc_u32 s5, s91, 0
	s_add_u32 s12, s90, 0x1e2ea00
	s_addc_u32 s13, s91, 0
	s_mov_b32 s8, 0
	v_mov_b32_e32 v3, 0
	s_mov_b64 s[14:15], 0x80
	s_mov_b64 s[16:17], 0x100
	s_mov_b64 s[18:19], 0x180
	v_mov_b32_e32 v132, 0x358637bd
	s_mov_b32 s26, 0x800000
	v_mbcnt_hi_u32_b32 v133, -1, v1
	s_mov_b32 s27, s96
	s_branch .LBB0_2109
